# P5 65th-panel tail: LN1 scale/shift loads for all four chunks issued with the partial loads instead of a load/wait/store ladder
# baseline (speedup 1.0000x reference)
.LBB0_869:
	v_lshl_add_u64 v[22:23], s[92:93], 0, v[14:15]
	v_lshl_add_u64 v[24:25], s[92:93], 0, v[16:17]
	v_add_co_u32_e32 v0, vcc, 0x7380000, v22
	s_nop 1
	v_addc_co_u32_e32 v1, vcc, 0, v23, vcc
	v_add_co_u32_e32 v2, vcc, 0x7480000, v22
	s_nop 1
	v_addc_co_u32_e32 v3, vcc, 0, v23, vcc
	v_add_co_u32_e32 v4, vcc, 0x7580000, v22
	s_nop 1
	v_addc_co_u32_e32 v5, vcc, 0, v23, vcc
	v_add_co_u32_e32 v6, vcc, 0x7680000, v22
	s_nop 1
	v_addc_co_u32_e32 v7, vcc, 0, v23, vcc
	v_add_co_u32_e32 v18, vcc, 0x1200000, v24
	s_nop 1
	v_addc_co_u32_e32 v19, vcc, 0, v25, vcc
	global_load_dwordx4 v[76:79], v[0:1], off
	global_load_dwordx4 v[92:95], v[2:3], off
	global_load_dwordx4 v[108:111], v[4:5], off
	global_load_dwordx4 v[124:127], v[6:7], off
	global_load_dwordx2 v[140:141], v[18:19], off
	global_load_dwordx4 v[148:151], v[8:9], off
	global_load_dwordx4 v[80:83], v[0:1], off offset:1024
	global_load_dwordx4 v[96:99], v[2:3], off offset:1024
	global_load_dwordx4 v[112:115], v[4:5], off offset:1024
	global_load_dwordx4 v[128:131], v[6:7], off offset:1024
	global_load_dwordx2 v[142:143], v[18:19], off offset:512
	global_load_dwordx4 v[152:155], v[8:9], off offset:1024
	global_load_dwordx4 v[84:87], v[0:1], off offset:2048
	global_load_dwordx4 v[100:103], v[2:3], off offset:2048
	global_load_dwordx4 v[116:119], v[4:5], off offset:2048
	global_load_dwordx4 v[132:135], v[6:7], off offset:2048
	global_load_dwordx2 v[144:145], v[18:19], off offset:1024
	global_load_dwordx4 v[156:159], v[8:9], off offset:2048
	global_load_dwordx4 v[88:91], v[0:1], off offset:3072
	global_load_dwordx4 v[104:107], v[2:3], off offset:3072
	global_load_dwordx4 v[120:123], v[4:5], off offset:3072
	global_load_dwordx4 v[136:139], v[6:7], off offset:3072
	global_load_dwordx2 v[146:147], v[18:19], off offset:1536
	global_load_dwordx4 v[160:163], v[8:9], off offset:3072
	global_load_dwordx4 v[190:193], v[10:11], off
	global_load_dwordx4 v[194:197], v[12:13], off
	global_load_dwordx4 v[198:201], v[10:11], off offset:1024
	global_load_dwordx4 v[202:205], v[12:13], off offset:1024
	global_load_dwordx4 v[206:209], v[10:11], off offset:2048
	global_load_dwordx4 v[210:213], v[12:13], off offset:2048
	global_load_dwordx4 v[214:217], v[10:11], off offset:3072
	global_load_dwordx4 v[226:229], v[12:13], off offset:3072
	s_mov_b32 s0, 0xf800000
	v_add_u32_e32 v48, s64, v48
	v_lshl_add_u64 v[14:15], v[14:15], 0, s[20:21]
	v_lshl_add_u64 v[16:17], v[16:17], 0, s[22:23]
	v_mov_b32_e32 v0, 0
	s_waitcnt vmcnt(26)
	v_pk_add_f32 v[76:77], v[76:77], v[92:93]
	v_pk_add_f32 v[78:79], v[78:79], v[94:95]
	v_pk_add_f32 v[76:77], v[76:77], v[108:109]
	v_pk_add_f32 v[78:79], v[78:79], v[110:111]
	v_pk_add_f32 v[76:77], v[76:77], v[124:125]
	v_pk_add_f32 v[78:79], v[78:79], v[126:127]
	v_lshlrev_b32_e32 v164, 16, v140
	v_and_b32_e32 v165, 0xffff0000, v140
	v_lshlrev_b32_e32 v166, 16, v141
	v_and_b32_e32 v167, 0xffff0000, v141
	v_pk_fma_f32 v[148:149], v[164:165], s[28:29], v[148:149] op_sel_hi:[1,0,1]
	v_pk_fma_f32 v[150:151], v[166:167], s[28:29], v[150:151] op_sel_hi:[1,0,1]
	v_pk_add_f32 v[20:21], v[76:77], v[148:149]
	v_pk_add_f32 v[22:23], v[78:79], v[150:151]
	v_add_f32_e32 v164, v20, v21
	v_add_f32_e32 v165, v22, v23
	v_add_f32_e32 v164, v164, v165
	v_add_f32_e32 v0, v0, v164
	s_waitcnt vmcnt(20)
	v_pk_add_f32 v[80:81], v[80:81], v[96:97]
	v_pk_add_f32 v[82:83], v[82:83], v[98:99]
	v_pk_add_f32 v[80:81], v[80:81], v[112:113]
	v_pk_add_f32 v[82:83], v[82:83], v[114:115]
	v_pk_add_f32 v[80:81], v[80:81], v[128:129]
	v_pk_add_f32 v[82:83], v[82:83], v[130:131]
	v_lshlrev_b32_e32 v164, 16, v142
	v_and_b32_e32 v165, 0xffff0000, v142
	v_lshlrev_b32_e32 v166, 16, v143
	v_and_b32_e32 v167, 0xffff0000, v143
	v_pk_fma_f32 v[152:153], v[164:165], s[28:29], v[152:153] op_sel_hi:[1,0,1]
	v_pk_fma_f32 v[154:155], v[166:167], s[28:29], v[154:155] op_sel_hi:[1,0,1]
	v_pk_add_f32 v[24:25], v[80:81], v[152:153]
	v_pk_add_f32 v[26:27], v[82:83], v[154:155]
	v_add_f32_e32 v164, v24, v25
	v_add_f32_e32 v165, v26, v27
	v_add_f32_e32 v164, v164, v165
	v_add_f32_e32 v0, v0, v164
	s_waitcnt vmcnt(14)
	v_pk_add_f32 v[84:85], v[84:85], v[100:101]
	v_pk_add_f32 v[86:87], v[86:87], v[102:103]
	v_pk_add_f32 v[84:85], v[84:85], v[116:117]
	v_pk_add_f32 v[86:87], v[86:87], v[118:119]
	v_pk_add_f32 v[84:85], v[84:85], v[132:133]
	v_pk_add_f32 v[86:87], v[86:87], v[134:135]
	v_lshlrev_b32_e32 v164, 16, v144
	v_and_b32_e32 v165, 0xffff0000, v144
	v_lshlrev_b32_e32 v166, 16, v145
	v_and_b32_e32 v167, 0xffff0000, v145
	v_pk_fma_f32 v[156:157], v[164:165], s[28:29], v[156:157] op_sel_hi:[1,0,1]
	v_pk_fma_f32 v[158:159], v[166:167], s[28:29], v[158:159] op_sel_hi:[1,0,1]
	v_pk_add_f32 v[28:29], v[84:85], v[156:157]
	v_pk_add_f32 v[30:31], v[86:87], v[158:159]
	v_add_f32_e32 v164, v28, v29
	v_add_f32_e32 v165, v30, v31
	v_add_f32_e32 v164, v164, v165
	v_add_f32_e32 v0, v0, v164
	s_waitcnt vmcnt(8)
	v_pk_add_f32 v[88:89], v[88:89], v[104:105]
	v_pk_add_f32 v[90:91], v[90:91], v[106:107]
	v_pk_add_f32 v[88:89], v[88:89], v[120:121]
	v_pk_add_f32 v[90:91], v[90:91], v[122:123]
	v_pk_add_f32 v[88:89], v[88:89], v[136:137]
	v_pk_add_f32 v[90:91], v[90:91], v[138:139]
	v_lshlrev_b32_e32 v164, 16, v146
	v_and_b32_e32 v165, 0xffff0000, v146
	v_lshlrev_b32_e32 v166, 16, v147
	v_and_b32_e32 v167, 0xffff0000, v147
	v_pk_fma_f32 v[160:161], v[164:165], s[28:29], v[160:161] op_sel_hi:[1,0,1]
	v_pk_fma_f32 v[162:163], v[166:167], s[28:29], v[162:163] op_sel_hi:[1,0,1]
	v_pk_add_f32 v[32:33], v[88:89], v[160:161]
	v_pk_add_f32 v[34:35], v[90:91], v[162:163]
	v_add_f32_e32 v164, v32, v33
	v_add_f32_e32 v165, v34, v35
	v_add_f32_e32 v164, v164, v165
	v_add_f32_e32 v0, v0, v164
	ds_bpermute_b32 v1, v40, v0
	s_waitcnt lgkmcnt(0)
	v_add_f32_e32 v0, v0, v1
	ds_bpermute_b32 v1, v41, v0
	s_waitcnt lgkmcnt(0)
	v_add_f32_e32 v0, v0, v1
	ds_bpermute_b32 v1, v42, v0
	s_waitcnt lgkmcnt(0)
	v_add_f32_e32 v0, v0, v1
	ds_bpermute_b32 v1, v43, v0
	s_waitcnt lgkmcnt(0)
	v_add_f32_e32 v0, v0, v1
	ds_bpermute_b32 v1, v44, v0
	s_waitcnt lgkmcnt(0)
	v_add_f32_e32 v0, v0, v1
	ds_bpermute_b32 v1, v45, v0
	s_waitcnt lgkmcnt(0)
	v_add_f32_e32 v36, v0, v1
	v_fmamk_f32 v21, v36, 0xba800000, v21
	v_fmac_f32_e32 v20, 0xba800000, v36
	v_fmamk_f32 v23, v36, 0xba800000, v23
	v_fmac_f32_e32 v22, 0xba800000, v36
	v_pk_mul_f32 v[0:1], v[22:23], v[22:23]
	v_pk_mul_f32 v[2:3], v[20:21], v[20:21]
	v_fmamk_f32 v25, v36, 0xba800000, v25
	v_pk_mov_b32 v[4:5], v[2:3], v[0:1] op_sel:[1,0]
	v_mov_b32_e32 v3, v1
	v_pk_add_f32 v[0:1], v[4:5], v[2:3]
	v_fmac_f32_e32 v24, 0xba800000, v36
	v_fmamk_f32 v27, v36, 0xba800000, v27
	v_fmac_f32_e32 v26, 0xba800000, v36
	v_pk_add_f32 v[0:1], v[0:1], v[0:1] op_sel_hi:[0,1]
	v_pk_mul_f32 v[2:3], v[26:27], v[26:27]
	v_pk_mul_f32 v[4:5], v[24:25], v[24:25]
	v_fmac_f32_e32 v28, 0xba800000, v36
	v_pk_mov_b32 v[6:7], v[4:5], v[2:3] op_sel:[1,0]
	v_mov_b32_e32 v5, v3
	v_fmamk_f32 v29, v36, 0xba800000, v29
	v_fmac_f32_e32 v30, 0xba800000, v36
	v_mul_f32_e32 v0, v28, v28
	v_pk_add_f32 v[2:3], v[6:7], v[4:5]
	v_fmamk_f32 v31, v36, 0xba800000, v31
	v_pk_fma_f32 v[4:5], v[28:29], v[28:29], v[0:1] op_sel_hi:[1,1,0]
	v_mul_f32_e32 v0, v30, v30
	v_pk_add_f32 v[2:3], v[2:3], v[2:3] op_sel_hi:[0,1]
	v_pk_fma_f32 v[6:7], v[30:31], v[30:31], v[0:1] op_sel_hi:[1,1,0]
	v_fmamk_f32 v35, v36, 0xba800000, v35
	v_fmac_f32_e32 v34, 0xba800000, v36
	v_fmamk_f32 v33, v36, 0xba800000, v33
	v_fmac_f32_e32 v32, 0xba800000, v36
	v_mul_f32_e32 v4, v32, v32
	v_mul_f32_e32 v6, v33, v33
	v_mul_f32_e32 v0, v34, v34
	v_mul_f32_e32 v2, v35, v35
	v_pk_add_f32 v[4:5], v[4:5], v[6:7]
	v_pk_add_f32 v[0:1], v[0:1], v[2:3]
	s_nop 0
	v_pk_add_f32 v[0:1], v[4:5], v[0:1]
	s_nop 0
	v_add_f32_e32 v0, v0, v1
	ds_bpermute_b32 v1, v40, v0
	s_waitcnt lgkmcnt(0)
	v_add_f32_e32 v0, v0, v1
	ds_bpermute_b32 v1, v41, v0
	s_waitcnt lgkmcnt(0)
	v_add_f32_e32 v0, v0, v1
	ds_bpermute_b32 v1, v42, v0
	s_waitcnt lgkmcnt(0)
	v_add_f32_e32 v0, v0, v1
	ds_bpermute_b32 v1, v43, v0
	s_waitcnt lgkmcnt(0)
	v_add_f32_e32 v0, v0, v1
	ds_bpermute_b32 v1, v44, v0
	s_waitcnt lgkmcnt(0)
	v_add_f32_e32 v0, v0, v1
	ds_bpermute_b32 v1, v45, v0
	s_waitcnt lgkmcnt(0)
	v_add_f32_e32 v0, v0, v1
	v_fmamk_f32 v0, v0, 0x3a800000, v46
	v_cmp_gt_f32_e32 vcc, s0, v0
	v_mul_f32_e32 v1, 0x4f800000, v0
	s_nop 0
	v_cndmask_b32_e32 v0, v0, v1, vcc
	v_sqrt_f32_e32 v1, v0
	s_nop 0
	v_add_u32_e32 v2, -1, v1
	v_fma_f32 v3, -v2, v1, v0
	v_cmp_ge_f32_e64 s[0:1], 0, v3
	v_add_u32_e32 v3, 1, v1
	s_nop 0
	v_cndmask_b32_e64 v2, v1, v2, s[0:1]
	v_fma_f32 v1, -v3, v1, v0
	v_cmp_lt_f32_e64 s[0:1], 0, v1
	s_nop 1
	v_cndmask_b32_e64 v1, v2, v3, s[0:1]
	v_mul_f32_e32 v2, 0x37800000, v1
	v_cndmask_b32_e32 v1, v1, v2, vcc
	v_cmp_class_f32_e32 vcc, v0, v47
	s_nop 1
	v_cndmask_b32_e32 v0, v1, v0, vcc
	v_div_scale_f32 v1, s[0:1], v0, v0, 1.0
	v_rcp_f32_e32 v2, v1
	s_movk_i32 s0, 0x40ff
	v_fma_f32 v3, -v1, v2, 1.0
	v_fmac_f32_e32 v2, v3, v2
	v_div_scale_f32 v3, vcc, 1.0, v0, 1.0
	v_mul_f32_e32 v4, v3, v2
	v_fma_f32 v5, -v1, v4, v3
	v_fmac_f32_e32 v4, v5, v2
	v_fma_f32 v1, -v1, v4, v3
	v_div_fmas_f32 v1, v1, v2, v4
	v_div_fixup_f32 v36, v1, v0, 1.0
	s_nop 0
	s_nop 0
	v_pk_mul_f32 v[20:21], v[20:21], v[36:37] op_sel_hi:[1,0]
	v_pk_mul_f32 v[22:23], v[22:23], v[36:37] op_sel_hi:[1,0]
	v_cmp_lt_i32_e32 vcc, s0, v48
	s_or_b64 s[26:27], vcc, s[26:27]
	s_waitcnt vmcnt(0)
	v_pk_fma_f32 v[0:1], v[190:191], v[20:21], v[194:195]
	v_pk_fma_f32 v[2:3], v[192:193], v[22:23], v[196:197]
	v_cvt_pk_bf16_f32 v0, v0, v1
	v_pk_mul_f32 v[20:21], v[24:25], v[36:37] op_sel_hi:[1,0]
	v_cvt_pk_bf16_f32 v1, v2, v3
	global_store_dwordx2 v[18:19], v[0:1], off
	s_nop 0
	s_nop 0
	s_nop 0
	v_pk_mul_f32 v[22:23], v[26:27], v[36:37] op_sel_hi:[1,0]
	s_nop 0
	v_pk_fma_f32 v[0:1], v[198:199], v[20:21], v[202:203]
	v_pk_fma_f32 v[2:3], v[200:201], v[22:23], v[204:205]
	v_cvt_pk_bf16_f32 v0, v0, v1
	v_pk_mul_f32 v[20:21], v[28:29], v[36:37] op_sel_hi:[1,0]
	v_cvt_pk_bf16_f32 v1, v2, v3
	global_store_dwordx2 v[18:19], v[0:1], off offset:512
	s_nop 0
	s_nop 0
	s_nop 0
	v_pk_mul_f32 v[22:23], v[30:31], v[36:37] op_sel_hi:[1,0]
	s_nop 0
	v_pk_fma_f32 v[0:1], v[206:207], v[20:21], v[210:211]
	v_pk_fma_f32 v[2:3], v[208:209], v[22:23], v[212:213]
	v_cvt_pk_bf16_f32 v0, v0, v1
	v_pk_mul_f32 v[20:21], v[32:33], v[36:37] op_sel_hi:[1,0]
	v_cvt_pk_bf16_f32 v1, v2, v3
	global_store_dwordx2 v[18:19], v[0:1], off offset:1024
	s_nop 0
	s_nop 0
	s_nop 0
	v_pk_mul_f32 v[22:23], v[34:35], v[36:37] op_sel_hi:[1,0]
	s_nop 0
	v_pk_fma_f32 v[0:1], v[214:215], v[20:21], v[226:227]
	v_pk_fma_f32 v[2:3], v[216:217], v[22:23], v[228:229]
	v_cvt_pk_bf16_f32 v0, v0, v1
	s_nop 0
	v_cvt_pk_bf16_f32 v1, v2, v3
	global_store_dwordx2 v[18:19], v[0:1], off offset:1536
	s_andn2_b64 exec, exec, s[26:27]
	s_cbranch_execnz .LBB0_869
